# attention: softmax exponentials of rows 1..7 issued under the PV phase's fragment reads/MFMAs (MFMA-VALU interleave), sum reduced after PV
# speedup vs baseline: 1.0068x; 1.0068x over previous
.Latt_vw_go:
	v_add_u32_e32 v0, 0x3c00, v231
	ds_write_b128 v0, v[4:7]
	ds_write_b128 v0, v[8:11] offset:9216
	v_add_u32_e32 v0, 0x8400, v231
	ds_write_b128 v0, v[12:15]
	ds_write_b128 v0, v[16:19] offset:9216
	v_add_u32_e32 v0, 0xcc00, v231
	ds_write_b128 v0, v[20:23]
	ds_write_b128 v0, v[24:27] offset:9216
	v_add_u32_e32 v0, 0x11400, v231
	ds_write_b128 v0, v[28:31]
	ds_write_b128 v0, v[32:35] offset:9216
	v_add_u32_e32 v0, 0x15c00, v231
	ds_write_b128 v0, v[36:39]
	ds_write_b128 v0, v[40:43] offset:9216
	v_add_u32_e32 v0, 0x1a400, v231
	ds_write_b128 v0, v[44:47]
	ds_write_b128 v0, v[48:51] offset:9216
	v_add_u32_e32 v0, 0x1ec00, v231
	ds_write_b128 v0, v[52:55]
	ds_write_b128 v0, v[56:59] offset:9216
	v_mov_b32_e32 v251, 0xf149f2ca
	v_mov_b32_e32 v252, 0x3db504f3
	v_mov_b32_e32 v254, 0x3fb8aa3b
	v_add_u32_e32 v156, s67, v240
	v_add_u32_e32 v157, s67, v241
	v_add_u32_e32 v158, s67, v242
	v_add_u32_e32 v159, s67, v243
	v_add_u32_e32 v160, s67, v244
	v_add_u32_e32 v161, s67, v245
	v_add_u32_e32 v162, s67, v246
	v_add_u32_e32 v163, s67, v247
	v_mov_b32_e32 v248, 0xff61b1e6
	ds_read_b32 v164, v156 offset:0
	ds_read_b32 v165, v157 offset:0
	ds_read_b32 v166, v158 offset:0
	ds_read_b32 v167, v159 offset:0
	ds_read_b32 v168, v160 offset:0
	ds_read_b32 v169, v161 offset:0
	ds_read_b32 v170, v162 offset:0
	ds_read_b32 v171, v163 offset:0
	s_waitcnt lgkmcnt(0)
	ds_read_b32 v172, v156 offset:124
	ds_read_b32 v173, v157 offset:124
	ds_read_b32 v174, v158 offset:124
	ds_read_b32 v175, v159 offset:124
	ds_read_b32 v176, v160 offset:124
	ds_read_b32 v177, v161 offset:124
	ds_read_b32 v178, v162 offset:124
	ds_read_b32 v179, v163 offset:124
	v_pk_fma_f32 v[92:93], v[92:93], v[252:253], v[164:165] op_sel_hi:[1,0,1]
	v_pk_fma_f32 v[94:95], v[94:95], v[252:253], v[166:167] op_sel_hi:[1,0,1]
	v_pk_fma_f32 v[96:97], v[96:97], v[252:253], v[168:169] op_sel_hi:[1,0,1]
	v_pk_fma_f32 v[98:99], v[98:99], v[252:253], v[170:171] op_sel_hi:[1,0,1]
	v_cndmask_b32_e64 v92, v251, v92, s[4:5]
	v_cndmask_b32_e64 v93, v251, v93, s[6:7]
	v_cndmask_b32_e64 v94, v251, v94, s[8:9]
	v_cndmask_b32_e64 v95, v251, v95, s[10:11]
	v_cndmask_b32_e64 v96, v251, v96, s[12:13]
	v_cndmask_b32_e64 v97, v251, v97, s[14:15]
	v_cndmask_b32_e64 v98, v251, v98, s[16:17]
	v_cndmask_b32_e64 v99, v251, v99, s[18:19]
	v_max3_f32 v248, v248, v92, v93
	v_max3_f32 v248, v248, v94, v95
	v_max3_f32 v248, v248, v96, v97
	v_max3_f32 v248, v248, v98, v99
	s_waitcnt lgkmcnt(0)
	ds_read_b32 v164, v156 offset:248
	ds_read_b32 v165, v157 offset:248
	ds_read_b32 v166, v158 offset:248
	ds_read_b32 v167, v159 offset:248
	ds_read_b32 v168, v160 offset:248
	ds_read_b32 v169, v161 offset:248
	ds_read_b32 v170, v162 offset:248
	ds_read_b32 v171, v163 offset:248
	v_pk_fma_f32 v[100:101], v[100:101], v[252:253], v[172:173] op_sel_hi:[1,0,1]
	v_pk_fma_f32 v[102:103], v[102:103], v[252:253], v[174:175] op_sel_hi:[1,0,1]
	v_pk_fma_f32 v[104:105], v[104:105], v[252:253], v[176:177] op_sel_hi:[1,0,1]
	v_pk_fma_f32 v[106:107], v[106:107], v[252:253], v[178:179] op_sel_hi:[1,0,1]
	v_cndmask_b32_e64 v100, v251, v100, s[4:5]
	v_cndmask_b32_e64 v101, v251, v101, s[6:7]
	v_cndmask_b32_e64 v102, v251, v102, s[8:9]
	v_cndmask_b32_e64 v103, v251, v103, s[10:11]
	v_cndmask_b32_e64 v104, v251, v104, s[12:13]
	v_cndmask_b32_e64 v105, v251, v105, s[14:15]
	v_cndmask_b32_e64 v106, v251, v106, s[16:17]
	v_cndmask_b32_e64 v107, v251, v107, s[18:19]
	v_max3_f32 v248, v248, v100, v101
	v_max3_f32 v248, v248, v102, v103
	v_max3_f32 v248, v248, v104, v105
	v_max3_f32 v248, v248, v106, v107
	s_waitcnt lgkmcnt(0)
	ds_read_b32 v172, v156 offset:372
	ds_read_b32 v173, v157 offset:372
	ds_read_b32 v174, v158 offset:372
	ds_read_b32 v175, v159 offset:372
	ds_read_b32 v176, v160 offset:372
	ds_read_b32 v177, v161 offset:372
	ds_read_b32 v178, v162 offset:372
	ds_read_b32 v179, v163 offset:372
	v_pk_fma_f32 v[108:109], v[108:109], v[252:253], v[164:165] op_sel_hi:[1,0,1]
	v_pk_fma_f32 v[110:111], v[110:111], v[252:253], v[166:167] op_sel_hi:[1,0,1]
	v_pk_fma_f32 v[112:113], v[112:113], v[252:253], v[168:169] op_sel_hi:[1,0,1]
	v_pk_fma_f32 v[114:115], v[114:115], v[252:253], v[170:171] op_sel_hi:[1,0,1]
	v_cndmask_b32_e64 v108, v251, v108, s[4:5]
	v_cndmask_b32_e64 v109, v251, v109, s[6:7]
	v_cndmask_b32_e64 v110, v251, v110, s[8:9]
	v_cndmask_b32_e64 v111, v251, v111, s[10:11]
	v_cndmask_b32_e64 v112, v251, v112, s[12:13]
	v_cndmask_b32_e64 v113, v251, v113, s[14:15]
	v_cndmask_b32_e64 v114, v251, v114, s[16:17]
	v_cndmask_b32_e64 v115, v251, v115, s[18:19]
	v_max3_f32 v248, v248, v108, v109
	v_max3_f32 v248, v248, v110, v111
	v_max3_f32 v248, v248, v112, v113
	v_max3_f32 v248, v248, v114, v115
	s_waitcnt lgkmcnt(0)
	ds_read_b32 v164, v156 offset:496
	ds_read_b32 v165, v157 offset:496
	ds_read_b32 v166, v158 offset:496
	ds_read_b32 v167, v159 offset:496
	ds_read_b32 v168, v160 offset:496
	ds_read_b32 v169, v161 offset:496
	ds_read_b32 v170, v162 offset:496
	ds_read_b32 v171, v163 offset:496
	v_pk_fma_f32 v[116:117], v[116:117], v[252:253], v[172:173] op_sel_hi:[1,0,1]
	v_pk_fma_f32 v[118:119], v[118:119], v[252:253], v[174:175] op_sel_hi:[1,0,1]
	v_pk_fma_f32 v[120:121], v[120:121], v[252:253], v[176:177] op_sel_hi:[1,0,1]
	v_pk_fma_f32 v[122:123], v[122:123], v[252:253], v[178:179] op_sel_hi:[1,0,1]
	v_cndmask_b32_e64 v116, v251, v116, s[4:5]
	v_cndmask_b32_e64 v117, v251, v117, s[6:7]
	v_cndmask_b32_e64 v118, v251, v118, s[8:9]
	v_cndmask_b32_e64 v119, v251, v119, s[10:11]
	v_cndmask_b32_e64 v120, v251, v120, s[12:13]
	v_cndmask_b32_e64 v121, v251, v121, s[14:15]
	v_cndmask_b32_e64 v122, v251, v122, s[16:17]
	v_cndmask_b32_e64 v123, v251, v123, s[18:19]
	v_max3_f32 v248, v248, v116, v117
	v_max3_f32 v248, v248, v118, v119
	v_max3_f32 v248, v248, v120, v121
	v_max3_f32 v248, v248, v122, v123
	s_waitcnt lgkmcnt(0)
	ds_read_b32 v172, v156 offset:620
	ds_read_b32 v173, v157 offset:620
	ds_read_b32 v174, v158 offset:620
	ds_read_b32 v175, v159 offset:620
	ds_read_b32 v176, v160 offset:620
	ds_read_b32 v177, v161 offset:620
	ds_read_b32 v178, v162 offset:620
	ds_read_b32 v179, v163 offset:620
	v_pk_fma_f32 v[124:125], v[124:125], v[252:253], v[164:165] op_sel_hi:[1,0,1]
	v_pk_fma_f32 v[126:127], v[126:127], v[252:253], v[166:167] op_sel_hi:[1,0,1]
	v_pk_fma_f32 v[128:129], v[128:129], v[252:253], v[168:169] op_sel_hi:[1,0,1]
	v_pk_fma_f32 v[130:131], v[130:131], v[252:253], v[170:171] op_sel_hi:[1,0,1]
	v_cndmask_b32_e64 v124, v251, v124, s[4:5]
	v_cndmask_b32_e64 v125, v251, v125, s[6:7]
	v_cndmask_b32_e64 v126, v251, v126, s[8:9]
	v_cndmask_b32_e64 v127, v251, v127, s[10:11]
	v_cndmask_b32_e64 v128, v251, v128, s[12:13]
	v_cndmask_b32_e64 v129, v251, v129, s[14:15]
	v_cndmask_b32_e64 v130, v251, v130, s[16:17]
	v_cndmask_b32_e64 v131, v251, v131, s[18:19]
	v_max3_f32 v248, v248, v124, v125
	v_max3_f32 v248, v248, v126, v127
	v_max3_f32 v248, v248, v128, v129
	v_max3_f32 v248, v248, v130, v131
	s_waitcnt lgkmcnt(0)
	ds_read_b32 v164, v156 offset:744
	ds_read_b32 v165, v157 offset:744
	ds_read_b32 v166, v158 offset:744
	ds_read_b32 v167, v159 offset:744
	ds_read_b32 v168, v160 offset:744
	ds_read_b32 v169, v161 offset:744
	ds_read_b32 v170, v162 offset:744
	ds_read_b32 v171, v163 offset:744
	v_pk_fma_f32 v[132:133], v[132:133], v[252:253], v[172:173] op_sel_hi:[1,0,1]
	v_pk_fma_f32 v[134:135], v[134:135], v[252:253], v[174:175] op_sel_hi:[1,0,1]
	v_pk_fma_f32 v[136:137], v[136:137], v[252:253], v[176:177] op_sel_hi:[1,0,1]
	v_pk_fma_f32 v[138:139], v[138:139], v[252:253], v[178:179] op_sel_hi:[1,0,1]
	v_cndmask_b32_e64 v132, v251, v132, s[4:5]
	v_cndmask_b32_e64 v133, v251, v133, s[6:7]
	v_cndmask_b32_e64 v134, v251, v134, s[8:9]
	v_cndmask_b32_e64 v135, v251, v135, s[10:11]
	v_cndmask_b32_e64 v136, v251, v136, s[12:13]
	v_cndmask_b32_e64 v137, v251, v137, s[14:15]
	v_cndmask_b32_e64 v138, v251, v138, s[16:17]
	v_cndmask_b32_e64 v139, v251, v139, s[18:19]
	v_max3_f32 v248, v248, v132, v133
	v_max3_f32 v248, v248, v134, v135
	v_max3_f32 v248, v248, v136, v137
	v_max3_f32 v248, v248, v138, v139
	s_waitcnt lgkmcnt(0)
	ds_read_b32 v172, v156 offset:868
	ds_read_b32 v173, v157 offset:868
	ds_read_b32 v174, v158 offset:868
	ds_read_b32 v175, v159 offset:868
	ds_read_b32 v176, v160 offset:868
	ds_read_b32 v177, v161 offset:868
	ds_read_b32 v178, v162 offset:868
	ds_read_b32 v179, v163 offset:868
	v_pk_fma_f32 v[140:141], v[140:141], v[252:253], v[164:165] op_sel_hi:[1,0,1]
	v_pk_fma_f32 v[142:143], v[142:143], v[252:253], v[166:167] op_sel_hi:[1,0,1]
	v_pk_fma_f32 v[144:145], v[144:145], v[252:253], v[168:169] op_sel_hi:[1,0,1]
	v_pk_fma_f32 v[146:147], v[146:147], v[252:253], v[170:171] op_sel_hi:[1,0,1]
	v_cndmask_b32_e64 v140, v251, v140, s[4:5]
	v_cndmask_b32_e64 v141, v251, v141, s[6:7]
	v_cndmask_b32_e64 v142, v251, v142, s[8:9]
	v_cndmask_b32_e64 v143, v251, v143, s[10:11]
	v_cndmask_b32_e64 v144, v251, v144, s[12:13]
	v_cndmask_b32_e64 v145, v251, v145, s[14:15]
	v_cndmask_b32_e64 v146, v251, v146, s[16:17]
	v_cndmask_b32_e64 v147, v251, v147, s[18:19]
	v_max3_f32 v248, v248, v140, v141
	v_max3_f32 v248, v248, v142, v143
	v_max3_f32 v248, v248, v144, v145
	v_max3_f32 v248, v248, v146, v147
	s_waitcnt lgkmcnt(0)
	v_pk_fma_f32 v[148:149], v[148:149], v[252:253], v[172:173] op_sel_hi:[1,0,1]
	v_pk_fma_f32 v[150:151], v[150:151], v[252:253], v[174:175] op_sel_hi:[1,0,1]
	v_pk_fma_f32 v[152:153], v[152:153], v[252:253], v[176:177] op_sel_hi:[1,0,1]
	v_pk_fma_f32 v[154:155], v[154:155], v[252:253], v[178:179] op_sel_hi:[1,0,1]
	v_cndmask_b32_e64 v148, v251, v148, s[4:5]
	v_cndmask_b32_e64 v149, v251, v149, s[6:7]
	v_cndmask_b32_e64 v150, v251, v150, s[8:9]
	v_cndmask_b32_e64 v151, v251, v151, s[10:11]
	v_cndmask_b32_e64 v152, v251, v152, s[12:13]
	v_cndmask_b32_e64 v153, v251, v153, s[14:15]
	v_cndmask_b32_e64 v154, v251, v154, s[16:17]
	v_cndmask_b32_e64 v155, v251, v155, s[18:19]
	v_max3_f32 v248, v248, v148, v149
	v_max3_f32 v248, v248, v150, v151
	v_max3_f32 v248, v248, v152, v153
	v_max3_f32 v248, v248, v154, v155
	ds_bpermute_b32 v0, v238, v248
	s_waitcnt lgkmcnt(0)
	v_max_f32_e32 v248, v248, v0
	ds_bpermute_b32 v0, v239, v248
	s_waitcnt lgkmcnt(0)
	v_max_f32_e32 v248, v248, v0
	v_mov_b32_e32 v2, 0
	v_mov_b32_e32 v3, 0
	v_pk_add_f32 v[92:93], v[92:93], v[248:249] op_sel_hi:[1,0] neg_lo:[0,1] neg_hi:[0,1]
	v_pk_add_f32 v[94:95], v[94:95], v[248:249] op_sel_hi:[1,0] neg_lo:[0,1] neg_hi:[0,1]
	v_pk_add_f32 v[96:97], v[96:97], v[248:249] op_sel_hi:[1,0] neg_lo:[0,1] neg_hi:[0,1]
	v_pk_add_f32 v[98:99], v[98:99], v[248:249] op_sel_hi:[1,0] neg_lo:[0,1] neg_hi:[0,1]
	v_pk_mul_f32 v[92:93], v[92:93], v[254:255] op_sel_hi:[1,0]
	v_pk_mul_f32 v[94:95], v[94:95], v[254:255] op_sel_hi:[1,0]
	v_pk_mul_f32 v[96:97], v[96:97], v[254:255] op_sel_hi:[1,0]
	v_pk_mul_f32 v[98:99], v[98:99], v[254:255] op_sel_hi:[1,0]
	v_exp_f32_e32 v92, v92
	v_exp_f32_e32 v93, v93
	v_exp_f32_e32 v94, v94
	v_exp_f32_e32 v95, v95
	v_exp_f32_e32 v96, v96
	v_exp_f32_e32 v97, v97
	v_exp_f32_e32 v98, v98
	v_exp_f32_e32 v99, v99
	s_nop 0
	v_pk_add_f32 v[2:3], v[2:3], v[92:93]
	v_pk_add_f32 v[2:3], v[2:3], v[94:95]
	v_pk_add_f32 v[2:3], v[2:3], v[96:97]
	v_pk_add_f32 v[2:3], v[2:3], v[98:99]
	s_barrier
	s_add_i32 s30, s20, s46
	s_cmpk_lt_i32 s30, 0x200
	s_cbranch_scc0 .Latt_nopf1
	s_and_b32 s69, s30, 7
	s_lshr_b32 s76, s30, 8
	s_lshl_b32 s69, s69, 1
	s_add_i32 s69, s69, s76
	s_lshl_b32 s69, s69, 12
	s_bfe_u32 s76, s30, 0x50003
	s_lshl_b32 s76, s76, 1
	s_add_i32 s77, s76, -4
	s_max_i32 s77, s77, 0
	s_min_i32 s77, s77, 56
	s_add_i32 s83, s76, -3
	s_max_i32 s83, s83, 0
	s_min_i32 s83, s83, 56
	s_add_i32 s83, s83, 8
	s_sub_i32 s83, s83, s77
	s_add_i32 s76, s76, s88
	s_lshl_b32 s77, s77, 6
	s_add_i32 s77, s77, s69
	s_lshl_b32 s77, s77, 8
	s_add_u32 s34, s50, s77
	s_addc_u32 s35, s51, 0
	s_add_u32 s34, s34, 0xe200000
	s_addc_u32 s35, s35, 0
	s_lshl_b32 s76, s76, 6
	s_add_i32 s76, s76, s69
	s_lshl_b32 s77, s92, 4
	s_add_i32 s76, s76, s77
	s_lshl_b32 s76, s76, 8
	s_add_u32 s36, s50, s76
	s_addc_u32 s37, s51, 0
	s_add_u32 s36, s36, 0xd200000
	s_addc_u32 s37, s37, 0
	global_load_dwordx4 v[76:79], v235, s[36:37] offset:0
	global_load_dwordx4 v[80:83], v235, s[36:37] offset:64
	global_load_dwordx4 v[84:87], v235, s[36:37] offset:128
	global_load_dwordx4 v[88:91], v235, s[36:37] offset:192
	global_load_dwordx4 v[4:7], v226, s[34:35]
	global_load_dwordx4 v[8:11], v227, s[34:35]
	s_add_u32 s34, s34, 0x4000
	s_addc_u32 s35, s35, 0
	global_load_dwordx4 v[12:15], v226, s[34:35]
	global_load_dwordx4 v[16:19], v227, s[34:35]
	s_add_u32 s34, s34, 0x4000
	s_addc_u32 s35, s35, 0
	global_load_dwordx4 v[20:23], v226, s[34:35]
	global_load_dwordx4 v[24:27], v227, s[34:35]
	s_add_u32 s34, s34, 0x4000
	s_addc_u32 s35, s35, 0
	global_load_dwordx4 v[28:31], v226, s[34:35]
	global_load_dwordx4 v[32:35], v227, s[34:35]
	s_add_u32 s34, s34, 0x4000
	s_addc_u32 s35, s35, 0
	global_load_dwordx4 v[36:39], v226, s[34:35]
	global_load_dwordx4 v[40:43], v227, s[34:35]
	s_add_u32 s34, s34, 0x4000
	s_addc_u32 s35, s35, 0
	global_load_dwordx4 v[44:47], v226, s[34:35]
	global_load_dwordx4 v[48:51], v227, s[34:35]
	s_add_u32 s34, s34, 0x4000
	s_addc_u32 s35, s35, 0
	global_load_dwordx4 v[52:55], v226, s[34:35]
	global_load_dwordx4 v[56:59], v227, s[34:35]
	s_add_u32 s34, s34, 0x4000
	s_addc_u32 s35, s35, 0
.Latt_nopf1:
	v_cvt_pk_bf16_f32 v220, v92, v93
	v_cvt_pk_bf16_f32 v221, v94, v95
	v_cvt_pk_bf16_f32 v222, v96, v97
	v_cvt_pk_bf16_f32 v223, v98, v99
	s_add_i32 s30, s27, 0
	s_add_i32 s31, s30, -7
	s_cmp_lt_i32 s30, 7
	s_cselect_b32 s30, s30, s31
	s_mul_i32 s30, s30, 0x4800
	s_add_i32 s30, s30, 0x3c00
	v_add_u32_e32 v0, s30, v233
	ds_read_b128 v[156:159], v0 offset:0
	ds_read_b128 v[160:163], v0 offset:2304
	ds_read_b128 v[164:167], v0 offset:4608
	ds_read_b128 v[168:171], v0 offset:6912
	ds_read_b128 v[172:175], v0 offset:9216
	ds_read_b128 v[176:179], v0 offset:11520
	ds_read_b128 v[180:183], v0 offset:13824
	ds_read_b128 v[184:187], v0 offset:16128
	v_pk_add_f32 v[100:101], v[100:101], v[248:249] op_sel_hi:[1,0] neg_lo:[0,1] neg_hi:[0,1]
	v_pk_add_f32 v[102:103], v[102:103], v[248:249] op_sel_hi:[1,0] neg_lo:[0,1] neg_hi:[0,1]
	v_pk_add_f32 v[104:105], v[104:105], v[248:249] op_sel_hi:[1,0] neg_lo:[0,1] neg_hi:[0,1]
	v_pk_add_f32 v[106:107], v[106:107], v[248:249] op_sel_hi:[1,0] neg_lo:[0,1] neg_hi:[0,1]
	v_pk_mul_f32 v[100:101], v[100:101], v[254:255] op_sel_hi:[1,0]
	v_pk_mul_f32 v[102:103], v[102:103], v[254:255] op_sel_hi:[1,0]
	v_pk_mul_f32 v[104:105], v[104:105], v[254:255] op_sel_hi:[1,0]
	v_pk_mul_f32 v[106:107], v[106:107], v[254:255] op_sel_hi:[1,0]
	v_exp_f32_e32 v100, v100
	v_exp_f32_e32 v101, v101
	v_exp_f32_e32 v102, v102
	v_exp_f32_e32 v103, v103
	v_exp_f32_e32 v104, v104
	v_exp_f32_e32 v105, v105
	v_exp_f32_e32 v106, v106
	v_exp_f32_e32 v107, v107
	s_nop 0
	v_pk_add_f32 v[2:3], v[2:3], v[100:101]
	v_pk_add_f32 v[2:3], v[2:3], v[102:103]
	v_pk_add_f32 v[2:3], v[2:3], v[104:105]
	v_pk_add_f32 v[2:3], v[2:3], v[106:107]
	s_waitcnt lgkmcnt(7)
	v_mfma_f32_16x16x32_bf16 v[188:191], v[156:159], v[220:223], 0
	s_waitcnt lgkmcnt(6)
	v_mfma_f32_16x16x32_bf16 v[192:195], v[160:163], v[220:223], 0
	s_waitcnt lgkmcnt(5)
	v_mfma_f32_16x16x32_bf16 v[196:199], v[164:167], v[220:223], 0
	s_waitcnt lgkmcnt(4)
	v_mfma_f32_16x16x32_bf16 v[200:203], v[168:171], v[220:223], 0
	s_waitcnt lgkmcnt(3)
	v_mfma_f32_16x16x32_bf16 v[204:207], v[172:175], v[220:223], 0
	s_waitcnt lgkmcnt(2)
	v_mfma_f32_16x16x32_bf16 v[208:211], v[176:179], v[220:223], 0
	s_waitcnt lgkmcnt(1)
	v_mfma_f32_16x16x32_bf16 v[212:215], v[180:183], v[220:223], 0
	s_waitcnt lgkmcnt(0)
	v_mfma_f32_16x16x32_bf16 v[216:219], v[184:187], v[220:223], 0
	v_cvt_pk_bf16_f32 v220, v100, v101
	v_cvt_pk_bf16_f32 v221, v102, v103
	v_cvt_pk_bf16_f32 v222, v104, v105
	v_cvt_pk_bf16_f32 v223, v106, v107
	s_add_i32 s30, s27, 1
	s_add_i32 s31, s30, -7
	s_cmp_lt_i32 s30, 7
	s_cselect_b32 s30, s30, s31
	s_mul_i32 s30, s30, 0x4800
	s_add_i32 s30, s30, 0x3c00
	v_add_u32_e32 v0, s30, v233
	ds_read_b128 v[156:159], v0 offset:0
	ds_read_b128 v[160:163], v0 offset:2304
	ds_read_b128 v[164:167], v0 offset:4608
	ds_read_b128 v[168:171], v0 offset:6912
	ds_read_b128 v[172:175], v0 offset:9216
	ds_read_b128 v[176:179], v0 offset:11520
	ds_read_b128 v[180:183], v0 offset:13824
	ds_read_b128 v[184:187], v0 offset:16128
	v_pk_add_f32 v[108:109], v[108:109], v[248:249] op_sel_hi:[1,0] neg_lo:[0,1] neg_hi:[0,1]
	v_pk_add_f32 v[110:111], v[110:111], v[248:249] op_sel_hi:[1,0] neg_lo:[0,1] neg_hi:[0,1]
	v_pk_add_f32 v[112:113], v[112:113], v[248:249] op_sel_hi:[1,0] neg_lo:[0,1] neg_hi:[0,1]
	v_pk_add_f32 v[114:115], v[114:115], v[248:249] op_sel_hi:[1,0] neg_lo:[0,1] neg_hi:[0,1]
	v_pk_mul_f32 v[108:109], v[108:109], v[254:255] op_sel_hi:[1,0]
	v_pk_mul_f32 v[110:111], v[110:111], v[254:255] op_sel_hi:[1,0]
	v_pk_mul_f32 v[112:113], v[112:113], v[254:255] op_sel_hi:[1,0]
	v_pk_mul_f32 v[114:115], v[114:115], v[254:255] op_sel_hi:[1,0]
	v_exp_f32_e32 v108, v108
	v_exp_f32_e32 v109, v109
	v_exp_f32_e32 v110, v110
	v_exp_f32_e32 v111, v111
	v_exp_f32_e32 v112, v112
	v_exp_f32_e32 v113, v113
	v_exp_f32_e32 v114, v114
	v_exp_f32_e32 v115, v115
	s_nop 0
	v_pk_add_f32 v[2:3], v[2:3], v[108:109]
	v_pk_add_f32 v[2:3], v[2:3], v[110:111]
	v_pk_add_f32 v[2:3], v[2:3], v[112:113]
	v_pk_add_f32 v[2:3], v[2:3], v[114:115]
	s_waitcnt lgkmcnt(7)
	v_mfma_f32_16x16x32_bf16 v[188:191], v[156:159], v[220:223], v[188:191]
	s_waitcnt lgkmcnt(6)
	v_mfma_f32_16x16x32_bf16 v[192:195], v[160:163], v[220:223], v[192:195]
	s_waitcnt lgkmcnt(5)
	v_mfma_f32_16x16x32_bf16 v[196:199], v[164:167], v[220:223], v[196:199]
	s_waitcnt lgkmcnt(4)
	v_mfma_f32_16x16x32_bf16 v[200:203], v[168:171], v[220:223], v[200:203]
	s_waitcnt lgkmcnt(3)
	v_mfma_f32_16x16x32_bf16 v[204:207], v[172:175], v[220:223], v[204:207]
	s_waitcnt lgkmcnt(2)
	v_mfma_f32_16x16x32_bf16 v[208:211], v[176:179], v[220:223], v[208:211]
	s_waitcnt lgkmcnt(1)
	v_mfma_f32_16x16x32_bf16 v[212:215], v[180:183], v[220:223], v[212:215]
	s_waitcnt lgkmcnt(0)
	v_mfma_f32_16x16x32_bf16 v[216:219], v[184:187], v[220:223], v[216:219]
	v_cvt_pk_bf16_f32 v220, v108, v109
	v_cvt_pk_bf16_f32 v221, v110, v111
	v_cvt_pk_bf16_f32 v222, v112, v113
	v_cvt_pk_bf16_f32 v223, v114, v115
	s_add_i32 s30, s27, 2
	s_add_i32 s31, s30, -7
	s_cmp_lt_i32 s30, 7
	s_cselect_b32 s30, s30, s31
	s_mul_i32 s30, s30, 0x4800
	s_add_i32 s30, s30, 0x3c00
	v_add_u32_e32 v0, s30, v233
	ds_read_b128 v[156:159], v0 offset:0
	ds_read_b128 v[160:163], v0 offset:2304
	ds_read_b128 v[164:167], v0 offset:4608
	ds_read_b128 v[168:171], v0 offset:6912
	ds_read_b128 v[172:175], v0 offset:9216
	ds_read_b128 v[176:179], v0 offset:11520
	ds_read_b128 v[180:183], v0 offset:13824
	ds_read_b128 v[184:187], v0 offset:16128
	v_pk_add_f32 v[116:117], v[116:117], v[248:249] op_sel_hi:[1,0] neg_lo:[0,1] neg_hi:[0,1]
	v_pk_add_f32 v[118:119], v[118:119], v[248:249] op_sel_hi:[1,0] neg_lo:[0,1] neg_hi:[0,1]
	v_pk_add_f32 v[120:121], v[120:121], v[248:249] op_sel_hi:[1,0] neg_lo:[0,1] neg_hi:[0,1]
	v_pk_add_f32 v[122:123], v[122:123], v[248:249] op_sel_hi:[1,0] neg_lo:[0,1] neg_hi:[0,1]
	v_pk_mul_f32 v[116:117], v[116:117], v[254:255] op_sel_hi:[1,0]
	v_pk_mul_f32 v[118:119], v[118:119], v[254:255] op_sel_hi:[1,0]
	v_pk_mul_f32 v[120:121], v[120:121], v[254:255] op_sel_hi:[1,0]
	v_pk_mul_f32 v[122:123], v[122:123], v[254:255] op_sel_hi:[1,0]
	v_exp_f32_e32 v116, v116
	v_exp_f32_e32 v117, v117
	v_exp_f32_e32 v118, v118
	v_exp_f32_e32 v119, v119
	v_exp_f32_e32 v120, v120
	v_exp_f32_e32 v121, v121
	v_exp_f32_e32 v122, v122
	v_exp_f32_e32 v123, v123
	s_nop 0
	v_pk_add_f32 v[2:3], v[2:3], v[116:117]
	v_pk_add_f32 v[2:3], v[2:3], v[118:119]
	v_pk_add_f32 v[2:3], v[2:3], v[120:121]
	v_pk_add_f32 v[2:3], v[2:3], v[122:123]
	s_waitcnt lgkmcnt(7)
	v_mfma_f32_16x16x32_bf16 v[188:191], v[156:159], v[220:223], v[188:191]
	s_waitcnt lgkmcnt(6)
	v_mfma_f32_16x16x32_bf16 v[192:195], v[160:163], v[220:223], v[192:195]
	s_waitcnt lgkmcnt(5)
	v_mfma_f32_16x16x32_bf16 v[196:199], v[164:167], v[220:223], v[196:199]
	s_waitcnt lgkmcnt(4)
	v_mfma_f32_16x16x32_bf16 v[200:203], v[168:171], v[220:223], v[200:203]
	s_waitcnt lgkmcnt(3)
	v_mfma_f32_16x16x32_bf16 v[204:207], v[172:175], v[220:223], v[204:207]
	s_waitcnt lgkmcnt(2)
	v_mfma_f32_16x16x32_bf16 v[208:211], v[176:179], v[220:223], v[208:211]
	s_waitcnt lgkmcnt(1)
	v_mfma_f32_16x16x32_bf16 v[212:215], v[180:183], v[220:223], v[212:215]
	s_waitcnt lgkmcnt(0)
	v_mfma_f32_16x16x32_bf16 v[216:219], v[184:187], v[220:223], v[216:219]
	v_cvt_pk_bf16_f32 v220, v116, v117
	v_cvt_pk_bf16_f32 v221, v118, v119
	v_cvt_pk_bf16_f32 v222, v120, v121
	v_cvt_pk_bf16_f32 v223, v122, v123
	s_add_i32 s30, s27, 3
	s_add_i32 s31, s30, -7
	s_cmp_lt_i32 s30, 7
	s_cselect_b32 s30, s30, s31
	s_mul_i32 s30, s30, 0x4800
	s_add_i32 s30, s30, 0x3c00
	v_add_u32_e32 v0, s30, v233
	ds_read_b128 v[156:159], v0 offset:0
	ds_read_b128 v[160:163], v0 offset:2304
	ds_read_b128 v[164:167], v0 offset:4608
	ds_read_b128 v[168:171], v0 offset:6912
	ds_read_b128 v[172:175], v0 offset:9216
	ds_read_b128 v[176:179], v0 offset:11520
	ds_read_b128 v[180:183], v0 offset:13824
	ds_read_b128 v[184:187], v0 offset:16128
	v_pk_add_f32 v[124:125], v[124:125], v[248:249] op_sel_hi:[1,0] neg_lo:[0,1] neg_hi:[0,1]
	v_pk_add_f32 v[126:127], v[126:127], v[248:249] op_sel_hi:[1,0] neg_lo:[0,1] neg_hi:[0,1]
	v_pk_add_f32 v[128:129], v[128:129], v[248:249] op_sel_hi:[1,0] neg_lo:[0,1] neg_hi:[0,1]
	v_pk_add_f32 v[130:131], v[130:131], v[248:249] op_sel_hi:[1,0] neg_lo:[0,1] neg_hi:[0,1]
	v_pk_mul_f32 v[124:125], v[124:125], v[254:255] op_sel_hi:[1,0]
	v_pk_mul_f32 v[126:127], v[126:127], v[254:255] op_sel_hi:[1,0]
	v_pk_mul_f32 v[128:129], v[128:129], v[254:255] op_sel_hi:[1,0]
	v_pk_mul_f32 v[130:131], v[130:131], v[254:255] op_sel_hi:[1,0]
	v_exp_f32_e32 v124, v124
	v_exp_f32_e32 v125, v125
	v_exp_f32_e32 v126, v126
	v_exp_f32_e32 v127, v127
	v_exp_f32_e32 v128, v128
	v_exp_f32_e32 v129, v129
	v_exp_f32_e32 v130, v130
	v_exp_f32_e32 v131, v131
	s_nop 0
	v_pk_add_f32 v[2:3], v[2:3], v[124:125]
	v_pk_add_f32 v[2:3], v[2:3], v[126:127]
	v_pk_add_f32 v[2:3], v[2:3], v[128:129]
	v_pk_add_f32 v[2:3], v[2:3], v[130:131]
	s_waitcnt lgkmcnt(7)
	v_mfma_f32_16x16x32_bf16 v[188:191], v[156:159], v[220:223], v[188:191]
	s_waitcnt lgkmcnt(6)
	v_mfma_f32_16x16x32_bf16 v[192:195], v[160:163], v[220:223], v[192:195]
	s_waitcnt lgkmcnt(5)
	v_mfma_f32_16x16x32_bf16 v[196:199], v[164:167], v[220:223], v[196:199]
	s_waitcnt lgkmcnt(4)
	v_mfma_f32_16x16x32_bf16 v[200:203], v[168:171], v[220:223], v[200:203]
	s_waitcnt lgkmcnt(3)
	v_mfma_f32_16x16x32_bf16 v[204:207], v[172:175], v[220:223], v[204:207]
	s_waitcnt lgkmcnt(2)
	v_mfma_f32_16x16x32_bf16 v[208:211], v[176:179], v[220:223], v[208:211]
	s_waitcnt lgkmcnt(1)
	v_mfma_f32_16x16x32_bf16 v[212:215], v[180:183], v[220:223], v[212:215]
	s_waitcnt lgkmcnt(0)
	v_mfma_f32_16x16x32_bf16 v[216:219], v[184:187], v[220:223], v[216:219]
	global_load_dwordx4 v[92:95], v237, s[60:61] offset:0
	global_load_dwordx4 v[96:99], v237, s[60:61] offset:64
	global_load_dwordx4 v[100:103], v237, s[60:61] offset:128
	global_load_dwordx4 v[104:107], v237, s[60:61] offset:192
	global_load_dwordx4 v[108:111], v237, s[60:61] offset:256
	global_load_dwordx4 v[112:115], v237, s[60:61] offset:320
	global_load_dwordx4 v[116:119], v237, s[60:61] offset:384
	global_load_dwordx4 v[120:123], v237, s[60:61] offset:448
	v_cvt_pk_bf16_f32 v220, v124, v125
	v_cvt_pk_bf16_f32 v221, v126, v127
	v_cvt_pk_bf16_f32 v222, v128, v129
	v_cvt_pk_bf16_f32 v223, v130, v131
	s_add_i32 s30, s27, 4
	s_add_i32 s31, s30, -7
	s_cmp_lt_i32 s30, 7
	s_cselect_b32 s30, s30, s31
	s_mul_i32 s30, s30, 0x4800
	s_add_i32 s30, s30, 0x3c00
	v_add_u32_e32 v0, s30, v233
	ds_read_b128 v[156:159], v0 offset:0
	ds_read_b128 v[160:163], v0 offset:2304
	ds_read_b128 v[164:167], v0 offset:4608
	ds_read_b128 v[168:171], v0 offset:6912
	ds_read_b128 v[172:175], v0 offset:9216
	ds_read_b128 v[176:179], v0 offset:11520
	ds_read_b128 v[180:183], v0 offset:13824
	ds_read_b128 v[184:187], v0 offset:16128
	v_pk_add_f32 v[132:133], v[132:133], v[248:249] op_sel_hi:[1,0] neg_lo:[0,1] neg_hi:[0,1]
	v_pk_add_f32 v[134:135], v[134:135], v[248:249] op_sel_hi:[1,0] neg_lo:[0,1] neg_hi:[0,1]
	v_pk_add_f32 v[136:137], v[136:137], v[248:249] op_sel_hi:[1,0] neg_lo:[0,1] neg_hi:[0,1]
	v_pk_add_f32 v[138:139], v[138:139], v[248:249] op_sel_hi:[1,0] neg_lo:[0,1] neg_hi:[0,1]
	v_pk_mul_f32 v[132:133], v[132:133], v[254:255] op_sel_hi:[1,0]
	v_pk_mul_f32 v[134:135], v[134:135], v[254:255] op_sel_hi:[1,0]
	v_pk_mul_f32 v[136:137], v[136:137], v[254:255] op_sel_hi:[1,0]
	v_pk_mul_f32 v[138:139], v[138:139], v[254:255] op_sel_hi:[1,0]
	v_exp_f32_e32 v132, v132
	v_exp_f32_e32 v133, v133
	v_exp_f32_e32 v134, v134
	v_exp_f32_e32 v135, v135
	v_exp_f32_e32 v136, v136
	v_exp_f32_e32 v137, v137
	v_exp_f32_e32 v138, v138
	v_exp_f32_e32 v139, v139
	s_nop 0
	v_pk_add_f32 v[2:3], v[2:3], v[132:133]
	v_pk_add_f32 v[2:3], v[2:3], v[134:135]
	v_pk_add_f32 v[2:3], v[2:3], v[136:137]
	v_pk_add_f32 v[2:3], v[2:3], v[138:139]
	s_waitcnt lgkmcnt(7)
	v_mfma_f32_16x16x32_bf16 v[188:191], v[156:159], v[220:223], v[188:191]
	s_waitcnt lgkmcnt(6)
	v_mfma_f32_16x16x32_bf16 v[192:195], v[160:163], v[220:223], v[192:195]
	s_waitcnt lgkmcnt(5)
	v_mfma_f32_16x16x32_bf16 v[196:199], v[164:167], v[220:223], v[196:199]
	s_waitcnt lgkmcnt(4)
	v_mfma_f32_16x16x32_bf16 v[200:203], v[168:171], v[220:223], v[200:203]
	s_waitcnt lgkmcnt(3)
	v_mfma_f32_16x16x32_bf16 v[204:207], v[172:175], v[220:223], v[204:207]
	s_waitcnt lgkmcnt(2)
	v_mfma_f32_16x16x32_bf16 v[208:211], v[176:179], v[220:223], v[208:211]
	s_waitcnt lgkmcnt(1)
	v_mfma_f32_16x16x32_bf16 v[212:215], v[180:183], v[220:223], v[212:215]
	s_waitcnt lgkmcnt(0)
	v_mfma_f32_16x16x32_bf16 v[216:219], v[184:187], v[220:223], v[216:219]
	v_cvt_pk_bf16_f32 v220, v132, v133
	v_cvt_pk_bf16_f32 v221, v134, v135
	v_cvt_pk_bf16_f32 v222, v136, v137
	v_cvt_pk_bf16_f32 v223, v138, v139
	s_add_i32 s30, s27, 5
	s_add_i32 s31, s30, -7
	s_cmp_lt_i32 s30, 7
	s_cselect_b32 s30, s30, s31
	s_mul_i32 s30, s30, 0x4800
	s_add_i32 s30, s30, 0x3c00
	v_add_u32_e32 v0, s30, v233
	ds_read_b128 v[156:159], v0 offset:0
	ds_read_b128 v[160:163], v0 offset:2304
	ds_read_b128 v[164:167], v0 offset:4608
	ds_read_b128 v[168:171], v0 offset:6912
	ds_read_b128 v[172:175], v0 offset:9216
	ds_read_b128 v[176:179], v0 offset:11520
	ds_read_b128 v[180:183], v0 offset:13824
	ds_read_b128 v[184:187], v0 offset:16128
	v_pk_add_f32 v[140:141], v[140:141], v[248:249] op_sel_hi:[1,0] neg_lo:[0,1] neg_hi:[0,1]
	v_pk_add_f32 v[142:143], v[142:143], v[248:249] op_sel_hi:[1,0] neg_lo:[0,1] neg_hi:[0,1]
	v_pk_add_f32 v[144:145], v[144:145], v[248:249] op_sel_hi:[1,0] neg_lo:[0,1] neg_hi:[0,1]
	v_pk_add_f32 v[146:147], v[146:147], v[248:249] op_sel_hi:[1,0] neg_lo:[0,1] neg_hi:[0,1]
	v_pk_mul_f32 v[140:141], v[140:141], v[254:255] op_sel_hi:[1,0]
	v_pk_mul_f32 v[142:143], v[142:143], v[254:255] op_sel_hi:[1,0]
	v_pk_mul_f32 v[144:145], v[144:145], v[254:255] op_sel_hi:[1,0]
	v_pk_mul_f32 v[146:147], v[146:147], v[254:255] op_sel_hi:[1,0]
	v_exp_f32_e32 v140, v140
	v_exp_f32_e32 v141, v141
	v_exp_f32_e32 v142, v142
	v_exp_f32_e32 v143, v143
	v_exp_f32_e32 v144, v144
	v_exp_f32_e32 v145, v145
	v_exp_f32_e32 v146, v146
	v_exp_f32_e32 v147, v147
	s_nop 0
	v_pk_add_f32 v[2:3], v[2:3], v[140:141]
	v_pk_add_f32 v[2:3], v[2:3], v[142:143]
	v_pk_add_f32 v[2:3], v[2:3], v[144:145]
	v_pk_add_f32 v[2:3], v[2:3], v[146:147]
	s_waitcnt lgkmcnt(7)
	v_mfma_f32_16x16x32_bf16 v[188:191], v[156:159], v[220:223], v[188:191]
	s_waitcnt lgkmcnt(6)
	v_mfma_f32_16x16x32_bf16 v[192:195], v[160:163], v[220:223], v[192:195]
	s_waitcnt lgkmcnt(5)
	v_mfma_f32_16x16x32_bf16 v[196:199], v[164:167], v[220:223], v[196:199]
	s_waitcnt lgkmcnt(4)
	v_mfma_f32_16x16x32_bf16 v[200:203], v[168:171], v[220:223], v[200:203]
	s_waitcnt lgkmcnt(3)
	v_mfma_f32_16x16x32_bf16 v[204:207], v[172:175], v[220:223], v[204:207]
	s_waitcnt lgkmcnt(2)
	v_mfma_f32_16x16x32_bf16 v[208:211], v[176:179], v[220:223], v[208:211]
	s_waitcnt lgkmcnt(1)
	v_mfma_f32_16x16x32_bf16 v[212:215], v[180:183], v[220:223], v[212:215]
	s_waitcnt lgkmcnt(0)
	v_mfma_f32_16x16x32_bf16 v[216:219], v[184:187], v[220:223], v[216:219]
	s_cmp_lg_u32 s27, 0
	s_cbranch_scc1 .Latt_p6a_skip
	v_cvt_pk_bf16_f32 v220, v140, v141
	v_cvt_pk_bf16_f32 v221, v142, v143
	v_cvt_pk_bf16_f32 v222, v144, v145
	v_cvt_pk_bf16_f32 v223, v146, v147
	s_add_i32 s30, s27, 6
	s_add_i32 s31, s30, -7
	s_cmp_lt_i32 s30, 7
	s_cselect_b32 s30, s30, s31
	s_mul_i32 s30, s30, 0x4800
	s_add_i32 s30, s30, 0x3c00
	v_add_u32_e32 v0, s30, v233
	ds_read_b128 v[156:159], v0 offset:0
	ds_read_b128 v[160:163], v0 offset:2304
	ds_read_b128 v[164:167], v0 offset:4608
	ds_read_b128 v[168:171], v0 offset:6912
	ds_read_b128 v[172:175], v0 offset:9216
	ds_read_b128 v[176:179], v0 offset:11520
	ds_read_b128 v[180:183], v0 offset:13824
	ds_read_b128 v[184:187], v0 offset:16128
	v_pk_add_f32 v[148:149], v[148:149], v[248:249] op_sel_hi:[1,0] neg_lo:[0,1] neg_hi:[0,1]
	v_pk_add_f32 v[150:151], v[150:151], v[248:249] op_sel_hi:[1,0] neg_lo:[0,1] neg_hi:[0,1]
	v_pk_add_f32 v[152:153], v[152:153], v[248:249] op_sel_hi:[1,0] neg_lo:[0,1] neg_hi:[0,1]
	v_pk_add_f32 v[154:155], v[154:155], v[248:249] op_sel_hi:[1,0] neg_lo:[0,1] neg_hi:[0,1]
	v_pk_mul_f32 v[148:149], v[148:149], v[254:255] op_sel_hi:[1,0]
	v_pk_mul_f32 v[150:151], v[150:151], v[254:255] op_sel_hi:[1,0]
	v_pk_mul_f32 v[152:153], v[152:153], v[254:255] op_sel_hi:[1,0]
	v_pk_mul_f32 v[154:155], v[154:155], v[254:255] op_sel_hi:[1,0]
	v_exp_f32_e32 v148, v148
	v_exp_f32_e32 v149, v149
	v_exp_f32_e32 v150, v150
	v_exp_f32_e32 v151, v151
	v_exp_f32_e32 v152, v152
	v_exp_f32_e32 v153, v153
	v_exp_f32_e32 v154, v154
	v_exp_f32_e32 v155, v155
	s_nop 0
	v_pk_add_f32 v[2:3], v[2:3], v[148:149]
	v_pk_add_f32 v[2:3], v[2:3], v[150:151]
	v_pk_add_f32 v[2:3], v[2:3], v[152:153]
	v_pk_add_f32 v[2:3], v[2:3], v[154:155]
	s_waitcnt lgkmcnt(7)
	v_mfma_f32_16x16x32_bf16 v[188:191], v[156:159], v[220:223], v[188:191]
	s_waitcnt lgkmcnt(6)
	v_mfma_f32_16x16x32_bf16 v[192:195], v[160:163], v[220:223], v[192:195]
	s_waitcnt lgkmcnt(5)
	v_mfma_f32_16x16x32_bf16 v[196:199], v[164:167], v[220:223], v[196:199]
	s_waitcnt lgkmcnt(4)
	v_mfma_f32_16x16x32_bf16 v[200:203], v[168:171], v[220:223], v[200:203]
	s_waitcnt lgkmcnt(3)
	v_mfma_f32_16x16x32_bf16 v[204:207], v[172:175], v[220:223], v[204:207]
	s_waitcnt lgkmcnt(2)
	v_mfma_f32_16x16x32_bf16 v[208:211], v[176:179], v[220:223], v[208:211]
	s_waitcnt lgkmcnt(1)
	v_mfma_f32_16x16x32_bf16 v[212:215], v[180:183], v[220:223], v[212:215]
	s_waitcnt lgkmcnt(0)
	v_mfma_f32_16x16x32_bf16 v[216:219], v[184:187], v[220:223], v[216:219]

.Latt_k8_skip_g:
.Latt_nopf3:
	s_cmp_eq_u32 s27, 0
	s_cbranch_scc1 .Latt_p6b_skip
	v_cvt_pk_bf16_f32 v220, v140, v141
	v_cvt_pk_bf16_f32 v221, v142, v143
	v_cvt_pk_bf16_f32 v222, v144, v145
	v_cvt_pk_bf16_f32 v223, v146, v147
	s_add_i32 s30, s27, 6
	s_add_i32 s31, s30, -7
	s_cmp_lt_i32 s30, 7
	s_cselect_b32 s30, s30, s31
	s_mul_i32 s30, s30, 0x4800
	s_add_i32 s30, s30, 0x3c00
	v_add_u32_e32 v0, s30, v233
	ds_read_b128 v[156:159], v0 offset:0
	ds_read_b128 v[160:163], v0 offset:2304
	ds_read_b128 v[164:167], v0 offset:4608
	ds_read_b128 v[168:171], v0 offset:6912
	ds_read_b128 v[172:175], v0 offset:9216
	ds_read_b128 v[176:179], v0 offset:11520
	ds_read_b128 v[180:183], v0 offset:13824
	ds_read_b128 v[184:187], v0 offset:16128
	v_pk_add_f32 v[148:149], v[148:149], v[248:249] op_sel_hi:[1,0] neg_lo:[0,1] neg_hi:[0,1]
	v_pk_add_f32 v[150:151], v[150:151], v[248:249] op_sel_hi:[1,0] neg_lo:[0,1] neg_hi:[0,1]
	v_pk_add_f32 v[152:153], v[152:153], v[248:249] op_sel_hi:[1,0] neg_lo:[0,1] neg_hi:[0,1]
	v_pk_add_f32 v[154:155], v[154:155], v[248:249] op_sel_hi:[1,0] neg_lo:[0,1] neg_hi:[0,1]
	v_pk_mul_f32 v[148:149], v[148:149], v[254:255] op_sel_hi:[1,0]
	v_pk_mul_f32 v[150:151], v[150:151], v[254:255] op_sel_hi:[1,0]
	v_pk_mul_f32 v[152:153], v[152:153], v[254:255] op_sel_hi:[1,0]
	v_pk_mul_f32 v[154:155], v[154:155], v[254:255] op_sel_hi:[1,0]
	v_exp_f32_e32 v148, v148
	v_exp_f32_e32 v149, v149
	v_exp_f32_e32 v150, v150
	v_exp_f32_e32 v151, v151
	v_exp_f32_e32 v152, v152
	v_exp_f32_e32 v153, v153
	v_exp_f32_e32 v154, v154
	v_exp_f32_e32 v155, v155
	s_nop 0
	v_pk_add_f32 v[2:3], v[2:3], v[148:149]
	v_pk_add_f32 v[2:3], v[2:3], v[150:151]
	v_pk_add_f32 v[2:3], v[2:3], v[152:153]
	v_pk_add_f32 v[2:3], v[2:3], v[154:155]
	s_waitcnt lgkmcnt(7)
	v_mfma_f32_16x16x32_bf16 v[188:191], v[156:159], v[220:223], v[188:191]
	s_waitcnt lgkmcnt(6)
	v_mfma_f32_16x16x32_bf16 v[192:195], v[160:163], v[220:223], v[192:195]
	s_waitcnt lgkmcnt(5)
	v_mfma_f32_16x16x32_bf16 v[196:199], v[164:167], v[220:223], v[196:199]
	s_waitcnt lgkmcnt(4)
	v_mfma_f32_16x16x32_bf16 v[200:203], v[168:171], v[220:223], v[200:203]
	s_waitcnt lgkmcnt(3)
	v_mfma_f32_16x16x32_bf16 v[204:207], v[172:175], v[220:223], v[204:207]
	s_waitcnt lgkmcnt(2)
	v_mfma_f32_16x16x32_bf16 v[208:211], v[176:179], v[220:223], v[208:211]
	s_waitcnt lgkmcnt(1)
	v_mfma_f32_16x16x32_bf16 v[212:215], v[180:183], v[220:223], v[212:215]
	s_waitcnt lgkmcnt(0)
	v_mfma_f32_16x16x32_bf16 v[216:219], v[184:187], v[220:223], v[216:219]
.Latt_p6b_skip:
	v_cvt_pk_bf16_f32 v220, v148, v149
	v_cvt_pk_bf16_f32 v221, v150, v151
	v_cvt_pk_bf16_f32 v222, v152, v153
	v_cvt_pk_bf16_f32 v223, v154, v155
	s_add_i32 s30, s27, 7
	s_add_i32 s31, s30, -7
	s_cmp_lt_i32 s30, 7
	s_cselect_b32 s30, s30, s31
	s_mul_i32 s30, s30, 0x4800
	s_add_i32 s30, s30, 0x3c00
	v_add_u32_e32 v0, s30, v233
	ds_read_b128 v[156:159], v0 offset:0
	ds_read_b128 v[160:163], v0 offset:2304
	ds_read_b128 v[164:167], v0 offset:4608
	ds_read_b128 v[168:171], v0 offset:6912
	ds_read_b128 v[172:175], v0 offset:9216
	ds_read_b128 v[176:179], v0 offset:11520
	ds_read_b128 v[180:183], v0 offset:13824
	ds_read_b128 v[184:187], v0 offset:16128
	s_waitcnt lgkmcnt(7)
	v_mfma_f32_16x16x32_bf16 v[188:191], v[156:159], v[220:223], v[188:191]
	s_waitcnt lgkmcnt(6)
	v_mfma_f32_16x16x32_bf16 v[192:195], v[160:163], v[220:223], v[192:195]
	s_waitcnt lgkmcnt(5)
	v_mfma_f32_16x16x32_bf16 v[196:199], v[164:167], v[220:223], v[196:199]
	s_waitcnt lgkmcnt(4)
	v_mfma_f32_16x16x32_bf16 v[200:203], v[168:171], v[220:223], v[200:203]
	s_waitcnt lgkmcnt(3)
	v_mfma_f32_16x16x32_bf16 v[204:207], v[172:175], v[220:223], v[204:207]
	s_waitcnt lgkmcnt(2)
	v_mfma_f32_16x16x32_bf16 v[208:211], v[176:179], v[220:223], v[208:211]
	s_waitcnt lgkmcnt(1)
	v_mfma_f32_16x16x32_bf16 v[212:215], v[180:183], v[220:223], v[212:215]
	s_waitcnt lgkmcnt(0)
	v_mfma_f32_16x16x32_bf16 v[216:219], v[184:187], v[220:223], v[216:219]
	v_add_f32_e32 v249, v2, v3
	ds_bpermute_b32 v0, v238, v249
	s_waitcnt lgkmcnt(0)
	v_add_f32_e32 v249, v249, v0
	ds_bpermute_b32 v0, v239, v249
	s_waitcnt lgkmcnt(0)
	v_add_f32_e32 v249, v249, v0
	v_div_scale_f32 v252, s[44:45], v249, v249, 1.0
	v_rcp_f32_e32 v253, v252
	v_div_scale_f32 v254, vcc, 1.0, v249, 1.0
	s_nop 0
	v_fma_f32 v255, -v252, v253, 1.0
	v_fmac_f32_e32 v253, v255, v253
	v_mul_f32_e32 v255, v254, v253
	v_fma_f32 v248, -v252, v255, v254
	v_fmac_f32_e32 v255, v248, v253
	v_fma_f32 v252, -v252, v255, v254
	v_div_fmas_f32 v252, v252, v253, v255
	v_div_fixup_f32 v252, v252, v249, 1.0
	s_nop 7
	v_pk_mul_f32 v[188:189], v[188:189], v[252:253] op_sel_hi:[1,0]
	v_pk_mul_f32 v[190:191], v[190:191], v[252:253] op_sel_hi:[1,0]
	v_pk_mul_f32 v[192:193], v[192:193], v[252:253] op_sel_hi:[1,0]
	v_pk_mul_f32 v[194:195], v[194:195], v[252:253] op_sel_hi:[1,0]
	v_pk_mul_f32 v[196:197], v[196:197], v[252:253] op_sel_hi:[1,0]
	v_pk_mul_f32 v[198:199], v[198:199], v[252:253] op_sel_hi:[1,0]
	v_pk_mul_f32 v[200:201], v[200:201], v[252:253] op_sel_hi:[1,0]
	v_pk_mul_f32 v[202:203], v[202:203], v[252:253] op_sel_hi:[1,0]
	v_pk_mul_f32 v[204:205], v[204:205], v[252:253] op_sel_hi:[1,0]
	v_pk_mul_f32 v[206:207], v[206:207], v[252:253] op_sel_hi:[1,0]
	v_pk_mul_f32 v[208:209], v[208:209], v[252:253] op_sel_hi:[1,0]
	v_pk_mul_f32 v[210:211], v[210:211], v[252:253] op_sel_hi:[1,0]
	v_pk_mul_f32 v[212:213], v[212:213], v[252:253] op_sel_hi:[1,0]
	v_pk_mul_f32 v[214:215], v[214:215], v[252:253] op_sel_hi:[1,0]
	v_pk_mul_f32 v[216:217], v[216:217], v[252:253] op_sel_hi:[1,0]
	v_pk_mul_f32 v[218:219], v[218:219], v[252:253] op_sel_hi:[1,0]
	v_pk_mul_f32 v[254:255], v[188:189], v[188:189]
	v_pk_fma_f32 v[254:255], v[190:191], v[190:191], v[254:255]
	v_pk_fma_f32 v[254:255], v[192:193], v[192:193], v[254:255]
	v_pk_fma_f32 v[254:255], v[194:195], v[194:195], v[254:255]
	v_pk_fma_f32 v[254:255], v[196:197], v[196:197], v[254:255]
	v_pk_fma_f32 v[254:255], v[198:199], v[198:199], v[254:255]
	v_pk_fma_f32 v[254:255], v[200:201], v[200:201], v[254:255]
	v_pk_fma_f32 v[254:255], v[202:203], v[202:203], v[254:255]
	v_pk_fma_f32 v[254:255], v[204:205], v[204:205], v[254:255]
	v_pk_fma_f32 v[254:255], v[206:207], v[206:207], v[254:255]
	v_pk_fma_f32 v[254:255], v[208:209], v[208:209], v[254:255]
	v_pk_fma_f32 v[254:255], v[210:211], v[210:211], v[254:255]
	v_pk_fma_f32 v[254:255], v[212:213], v[212:213], v[254:255]
	v_pk_fma_f32 v[254:255], v[214:215], v[214:215], v[254:255]
	v_pk_fma_f32 v[254:255], v[216:217], v[216:217], v[254:255]
	v_pk_fma_f32 v[254:255], v[218:219], v[218:219], v[254:255]
	v_add_f32_e32 v254, v254, v255
	ds_bpermute_b32 v253, v238, v254
	s_waitcnt lgkmcnt(0)
	v_add_f32_e32 v254, v254, v253
	ds_bpermute_b32 v253, v239, v254
	s_waitcnt lgkmcnt(0)
	v_add_f32_e32 v254, v254, v253
	v_mov_b32_e32 v253, 0x358637bd
	s_mov_b32 s30, 0x800000
	v_fmamk_f32 v254, v254, 0x3c000000, v253
	v_mul_f32_e32 v253, 0x4b800000, v254
	v_cmp_gt_f32_e32 vcc, s30, v254
	s_nop 1
	v_cndmask_b32_e32 v254, v254, v253, vcc
	v_rsq_f32_e32 v254, v254
	s_nop 0
	v_mul_f32_e32 v253, 0x45800000, v254
	v_cndmask_b32_e32 v254, v254, v253, vcc
	s_add_i32 s30, s20, s46
	s_cmpk_lt_i32 s30, 0x200
	s_cbranch_scc0 .Latt_nopf4
	s_waitcnt vmcnt(2)
	s_branch .Latt_gn_ok
